# v11 + next-row prefetch issued earlier in the T1/T3 row loops
# baseline (speedup 1.0000x reference)
; __device__ __forceinline__ void resid_rows(const float* xf_, bf16_t* XB_, const bf16_t* Y_, const float* gain_, float* R_, float* outf_, int rows, int gw, int NGW, int lane) {
;     ...
;     for (int row = gw; row < rows; row += NGW) {
;         RR_LOAD(nxw, nyw, nxv, row + NGW);
;         float v[16];
;         if (xf_) {
; #pragma unroll
;             for (int j = 0; j < 2; ++j) { const f32x4 a = xv[2 * j], b = xv[2 * j + 1];
;                 v[8 * j + 0] = a.x; v[8 * j + 1] = a.y; v[8 * j + 2] = a.z; v[8 * j + 3] = a.w; v[8 * j + 4] = b.x; v[8 * j + 5] = b.y; v[8 * j + 6] = b.z; v[8 * j + 7] = b.w; } }
;         else {
; #pragma unroll
;             for (int j = 0; j < 2; ++j) { const u32x4 w = xw[j];
;                 v[8 * j + 0] = bf_lo(w.x); v[8 * j + 1] = bf_hi(w.x); v[8 * j + 2] = bf_lo(w.y); v[8 * j + 3] = bf_hi(w.y); v[8 * j + 4] = bf_lo(w.z); v[8 * j + 5] = bf_hi(w.z); v[8 * j + 6] = bf_lo(w.w); v[8 * j + 7] = bf_hi(w.w); } }
;         if (Y_) { float y[16]; float ss = 0.f;
; #pragma unroll
;             for (int j = 0; j < 2; ++j) { const u32x4 w = yw[j];
;                 y[8 * j + 0] = bf_lo(w.x); y[8 * j + 1] = bf_hi(w.x); y[8 * j + 2] = bf_lo(w.y); y[8 * j + 3] = bf_hi(w.y); y[8 * j + 4] = bf_lo(w.z); y[8 * j + 5] = bf_hi(w.z); y[8 * j + 6] = bf_lo(w.w); y[8 * j + 7] = bf_hi(w.w); }
; #pragma unroll
;             for (int i = 0; i < 16; ++i) ss += y[i] * y[i];
;             const float r = 1.0f / sqrtf(wave_sum(ss) * (1.f / DM) + EPS);
;             const GASF f32x4* gp = (const GASF f32x4*)gain_;
; #pragma unroll
;             for (int j = 0; j < 2; ++j) { const f32x4 a = gp[lane * 2 + 128 * j], b = gp[lane * 2 + 1 + 128 * j];
;                 v[8 * j + 0] += y[8 * j + 0] * r * a.x; v[8 * j + 1] += y[8 * j + 1] * r * a.y; v[8 * j + 2] += y[8 * j + 2] * r * a.z; v[8 * j + 3] += y[8 * j + 3] * r * a.w;
;                 v[8 * j + 4] += y[8 * j + 4] * r * b.x; v[8 * j + 5] += y[8 * j + 5] * r * b.y; v[8 * j + 6] += y[8 * j + 6] * r * b.z; v[8 * j + 7] += y[8 * j + 7] * r * b.w; } }
;         if (outf_) { GASF f32x4* p = (GASF f32x4*)(outf_ + (size_t)row * DM);
; #pragma unroll
;             for (int j = 0; j < 2; ++j) { p[lane * 2 + 128 * j] = (f32x4){v[8 * j + 0], v[8 * j + 1], v[8 * j + 2], v[8 * j + 3]}; p[lane * 2 + 1 + 128 * j] = (f32x4){v[8 * j + 4], v[8 * j + 5], v[8 * j + 6], v[8 * j + 7]}; } }
.LBB0_199:
	s_waitcnt vmcnt(3)
	v_mov_b64_e32 v[18:19], v[14:15]
	v_mov_b64_e32 v[16:17], v[12:13]
	v_and_b32_e32 v54, 0xffff0000, v16
	v_lshlrev_b32_e32 v53, 16, v16
	v_mul_f32_e32 v16, v54, v54
	v_lshlrev_b32_e32 v55, 16, v17
	v_fmac_f32_e32 v16, v53, v53
	v_and_b32_e32 v56, 0xffff0000, v17
	v_fmac_f32_e32 v16, v55, v55
	v_lshlrev_b32_e32 v57, 16, v18
	v_fmac_f32_e32 v16, v56, v56
	v_and_b32_e32 v58, 0xffff0000, v18
	v_fmac_f32_e32 v16, v57, v57
	v_mov_b64_e32 v[22:23], v[6:7]
	v_lshlrev_b32_e32 v59, 16, v19
	v_fmac_f32_e32 v16, v58, v58
	v_mov_b64_e32 v[20:21], v[4:5]
	v_and_b32_e32 v60, 0xffff0000, v19
	v_fmac_f32_e32 v16, v59, v59
	v_lshlrev_b32_e32 v51, 16, v20
	v_fmac_f32_e32 v16, v60, v60
	v_and_b32_e32 v50, 0xffff0000, v20
	v_fmac_f32_e32 v16, v51, v51
	v_mov_b64_e32 v[30:31], v[10:11]
	v_lshlrev_b32_e32 v49, 16, v21
	v_fmac_f32_e32 v16, v50, v50
	v_mov_b64_e32 v[28:29], v[8:9]
	v_mov_b64_e32 v[46:47], v[2:3]
	v_and_b32_e32 v48, 0xffff0000, v21
	v_fmac_f32_e32 v16, v49, v49
	v_lshlrev_b32_e32 v41, 16, v28
	v_and_b32_e32 v43, 0xffff0000, v28
	v_lshlrev_b32_e32 v42, 16, v29
	v_and_b32_e32 v40, 0xffff0000, v29
	v_lshlrev_b32_e32 v29, 16, v47
	v_and_b32_e32 v28, 0xffff0000, v47
	v_lshlrev_b32_e32 v47, 16, v22
	v_fmac_f32_e32 v16, v48, v48
	v_mov_b64_e32 v[44:45], v[0:1]
	s_add_i32 s1, s1, s2
	s_min_i32 s28, s1, 0x7fff
	s_ashr_i32 s29, s28, 31
	s_lshl_b64 s[28:29], s[28:29], 11
	s_add_u32 s30, s4, s28
	s_addc_u32 s31, s5, s29
	s_add_u32 s28, s7, s28
	s_addc_u32 s29, s8, s29
	v_lshl_add_u64 v[4:5], s[28:29], 0, v[24:25]
	v_lshl_add_u64 v[0:1], s[30:31], 0, v[24:25]
	global_load_dwordx4 v[8:11], v[0:1], off
	s_nop 0
	global_load_dwordx4 v[0:3], v[0:1], off offset:1024
	s_nop 0
	global_load_dwordx4 v[12:15], v[4:5], off
	s_nop 0
	global_load_dwordx4 v[4:7], v[4:5], off offset:1024
	v_lshlrev_b32_e32 v39, 16, v30
	v_and_b32_e32 v38, 0xffff0000, v30
	v_lshlrev_b32_e32 v37, 16, v31
	v_and_b32_e32 v36, 0xffff0000, v31
	v_lshlrev_b32_e32 v31, 16, v46
	v_and_b32_e32 v30, 0xffff0000, v46
	v_and_b32_e32 v46, 0xffff0000, v22
	v_fmac_f32_e32 v16, v47, v47
	v_lshlrev_b32_e32 v33, 16, v45
	v_and_b32_e32 v32, 0xffff0000, v45
	v_lshlrev_b32_e32 v45, 16, v23
	v_fmac_f32_e32 v16, v46, v46
	v_lshlrev_b32_e32 v35, 16, v44
	v_and_b32_e32 v34, 0xffff0000, v44
	v_and_b32_e32 v44, 0xffff0000, v23
	v_fmac_f32_e32 v16, v45, v45
	v_fmac_f32_e32 v16, v44, v44
	ds_swizzle_b32 v17, v16 offset:swizzle(SWAP,1)
	s_waitcnt lgkmcnt(0)
	v_add_f32_e32 v16, v16, v17
	ds_swizzle_b32 v17, v16 offset:swizzle(SWAP,2)
	s_waitcnt lgkmcnt(0)
	v_add_f32_e32 v16, v16, v17
	ds_swizzle_b32 v17, v16 offset:swizzle(SWAP,4)
	s_waitcnt lgkmcnt(0)
	v_add_f32_e32 v16, v16, v17
	ds_swizzle_b32 v17, v16 offset:swizzle(SWAP,8)
	s_waitcnt lgkmcnt(0)
	v_add_f32_e32 v16, v16, v17
	ds_swizzle_b32 v17, v16 offset:swizzle(SWAP,16)
	s_waitcnt lgkmcnt(0)
	v_add_f32_e32 v16, v16, v17
	v_mov_b32_e32 v17, v16
	s_nop 1
	v_permlane32_swap_b32_e32 v16, v17
	v_add_f32_e32 v16, v16, v17
	v_fmamk_f32 v16, v16, 0x3a800000, v204
	v_cmp_gt_f32_e32 vcc, s81, v16
	v_mul_f32_e32 v17, 0x4f800000, v16
	s_nop 0
	v_cndmask_b32_e32 v16, v16, v17, vcc
	v_sqrt_f32_e32 v17, v16
	s_nop 0
	v_add_u32_e32 v18, -1, v17
	v_fma_f32 v19, -v18, v17, v16
	v_cmp_ge_f32_e64 s[42:43], 0, v19
	v_add_u32_e32 v19, 1, v17
	s_nop 0
	v_cndmask_b32_e64 v18, v17, v18, s[42:43]
	v_fma_f32 v17, -v19, v17, v16
	v_cmp_lt_f32_e64 s[42:43], 0, v17
	s_nop 1
	v_cndmask_b32_e64 v17, v18, v19, s[42:43]
	v_mul_f32_e32 v18, 0x37800000, v17
	v_cndmask_b32_e32 v17, v17, v18, vcc
	v_cmp_class_f32_e32 vcc, v16, v205
	s_nop 1
	v_cndmask_b32_e32 v16, v17, v16, vcc
	v_div_scale_f32 v17, s[28:29], v16, v16, 1.0
	v_rcp_f32_e32 v18, v17
	s_nop 0
	v_fma_f32 v19, -v17, v18, 1.0
	v_fmac_f32_e32 v18, v19, v18
	v_div_scale_f32 v19, vcc, 1.0, v16, 1.0
	v_mul_f32_e32 v20, v19, v18
	v_fma_f32 v21, -v17, v20, v19
	v_fmac_f32_e32 v20, v21, v18
	v_fma_f32 v17, -v17, v20, v19
	v_div_fmas_f32 v17, v17, v18, v20
	v_div_fixup_f32 v52, v17, v16, 1.0
	v_mul_f32_e32 v53, v52, v53
	v_mul_f32_e32 v51, v52, v51
	v_fmac_f32_e32 v41, v68, v53
	v_mul_f32_e32 v20, v52, v54
	v_fmac_f32_e32 v43, v69, v20
	v_mul_f32_e32 v20, v52, v55
	v_fmac_f32_e32 v42, v70, v20
	v_mul_f32_e32 v20, v52, v56
	v_fmac_f32_e32 v40, v71, v20
	v_mul_f32_e32 v20, v52, v57
	v_fmac_f32_e32 v39, v72, v20
	v_mul_f32_e32 v16, v52, v58
	v_fmac_f32_e32 v38, v73, v16
	v_mul_f32_e32 v16, v52, v59
	v_fmac_f32_e32 v37, v74, v16
	v_mul_f32_e32 v16, v52, v60
	v_fmac_f32_e32 v36, v75, v16
	v_fmac_f32_e32 v35, v76, v51
	v_mul_f32_e32 v20, v52, v50
	v_fmac_f32_e32 v34, v77, v20
	v_mul_f32_e32 v20, v52, v49
	v_fmac_f32_e32 v33, v78, v20
	v_mul_f32_e32 v22, v43, v43
	v_fmac_f32_e32 v22, v41, v41
	v_fmac_f32_e32 v22, v42, v42
	v_fmac_f32_e32 v22, v40, v40
	v_fmac_f32_e32 v22, v39, v39
	v_fmac_f32_e32 v22, v38, v38
	v_fmac_f32_e32 v22, v37, v37
	v_fmac_f32_e32 v22, v36, v36
	v_fmac_f32_e32 v22, v35, v35
	v_mul_f32_e32 v20, v52, v48
	v_fmac_f32_e32 v22, v34, v34
	v_fmac_f32_e32 v32, v79, v20
	v_mul_f32_e32 v20, v52, v47
	v_fmac_f32_e32 v22, v33, v33
	v_fmac_f32_e32 v31, v80, v20
	v_mul_f32_e32 v16, v52, v46
	v_fmac_f32_e32 v22, v32, v32
	v_fmac_f32_e32 v30, v81, v16
	v_mul_f32_e32 v16, v52, v45
	v_fmac_f32_e32 v22, v31, v31
	v_fmac_f32_e32 v29, v82, v16
	v_mul_f32_e32 v16, v52, v44
	v_fmac_f32_e32 v22, v30, v30
	v_fmac_f32_e32 v28, v83, v16
	v_cvt_pk_bf16_f32 v16, v41, v43
	v_lshl_add_u64 v[20:21], s[16:17], 0, v[24:25]
	v_fmac_f32_e32 v22, v29, v29
	v_cvt_pk_bf16_f32 v17, v42, v40
	v_cvt_pk_bf16_f32 v18, v39, v38
	v_cvt_pk_bf16_f32 v19, v37, v36
	global_store_dwordx4 v[20:21], v[16:19], off
	v_fmac_f32_e32 v22, v28, v28
	s_nop 0
	v_cvt_pk_bf16_f32 v16, v35, v34
	v_cvt_pk_bf16_f32 v17, v33, v32
	v_cvt_pk_bf16_f32 v18, v31, v30
	v_cvt_pk_bf16_f32 v19, v29, v28
	global_store_dwordx4 v[20:21], v[16:19], off offset:1024
	ds_swizzle_b32 v16, v22 offset:swizzle(SWAP,1)
	s_waitcnt lgkmcnt(0)
	v_add_f32_e32 v16, v22, v16
	ds_swizzle_b32 v17, v16 offset:swizzle(SWAP,2)
	s_waitcnt lgkmcnt(0)
	v_add_f32_e32 v16, v16, v17
	ds_swizzle_b32 v17, v16 offset:swizzle(SWAP,4)
	s_waitcnt lgkmcnt(0)
	v_add_f32_e32 v16, v16, v17
	ds_swizzle_b32 v17, v16 offset:swizzle(SWAP,8)
	s_waitcnt lgkmcnt(0)
	v_add_f32_e32 v16, v16, v17
	ds_swizzle_b32 v17, v16 offset:swizzle(SWAP,16)
	s_waitcnt lgkmcnt(0)
	v_add_f32_e32 v16, v16, v17
	v_mov_b32_e32 v17, v16
	s_nop 1
	v_permlane32_swap_b32_e32 v16, v17
	s_and_saveexec_b64 s[28:29], s[40:41]
	s_cbranch_execz .LBB0_198
; #define GASF __attribute__((address_space(1)))
; __device__ __forceinline__ void resid_rows(const float* xf_, bf16_t* XB_, const bf16_t* Y_, const float* gain_, float* R_, float* outf_, int rows, int gw, int NGW, int lane) {
;     ...
;             ss = wave_sum(ss);
;             if (lane == 0) ((GASF float*)R_)[row] = 1.0f / sqrtf(ss * (1.f / DM) + EPS); }
	v_add_f32_e32 v16, v16, v17
	v_fmamk_f32 v16, v16, 0x3a800000, v204
	v_mul_f32_e32 v17, 0x4f800000, v16
	v_cmp_gt_f32_e32 vcc, s81, v16
	s_nop 1
	v_cndmask_b32_e32 v16, v16, v17, vcc
	v_sqrt_f32_e32 v17, v16
	s_nop 0
	v_add_u32_e32 v18, -1, v17
	v_fma_f32 v20, -v18, v17, v16
	v_add_u32_e32 v19, 1, v17
	v_cmp_ge_f32_e64 s[42:43], 0, v20
	s_nop 1
	v_cndmask_b32_e64 v18, v17, v18, s[42:43]
	v_fma_f32 v17, -v19, v17, v16
	v_cmp_lt_f32_e64 s[42:43], 0, v17
	s_nop 1
	v_cndmask_b32_e64 v17, v18, v19, s[42:43]
	v_mul_f32_e32 v18, 0x37800000, v17
	v_cndmask_b32_e32 v17, v17, v18, vcc
	v_cmp_class_f32_e32 vcc, v16, v205
	s_nop 1
	v_cndmask_b32_e32 v16, v17, v16, vcc
	v_div_scale_f32 v17, s[30:31], v16, v16, 1.0
	v_rcp_f32_e32 v18, v17
	s_nop 0
	v_fma_f32 v19, -v17, v18, 1.0
	v_fmac_f32_e32 v18, v19, v18
	v_div_scale_f32 v19, vcc, 1.0, v16, 1.0
	v_mul_f32_e32 v20, v19, v18
	v_fma_f32 v21, -v17, v20, v19
	v_fmac_f32_e32 v20, v21, v18
	v_fma_f32 v17, -v17, v20, v19
	v_div_fmas_f32 v17, v17, v18, v20
	v_div_fixup_f32 v16, v17, v16, 1.0
	global_store_dword v175, v16, s[18:19]
	s_branch .LBB0_198

; __device__ __forceinline__ void resid_rows(const float* xf_, bf16_t* XB_, const bf16_t* Y_, const float* gain_, float* R_, float* outf_, int rows, int gw, int NGW, int lane) {
;     ...
;     for (int row = gw; row < rows; row += NGW) {
;         RR_LOAD(nxw, nyw, nxv, row + NGW);
;         float v[16];
;         if (xf_) {
; #pragma unroll
;             for (int j = 0; j < 2; ++j) { const f32x4 a = xv[2 * j], b = xv[2 * j + 1];
;                 v[8 * j + 0] = a.x; v[8 * j + 1] = a.y; v[8 * j + 2] = a.z; v[8 * j + 3] = a.w; v[8 * j + 4] = b.x; v[8 * j + 5] = b.y; v[8 * j + 6] = b.z; v[8 * j + 7] = b.w; } }
;         else {
; #pragma unroll
;             for (int j = 0; j < 2; ++j) { const u32x4 w = xw[j];
;                 v[8 * j + 0] = bf_lo(w.x); v[8 * j + 1] = bf_hi(w.x); v[8 * j + 2] = bf_lo(w.y); v[8 * j + 3] = bf_hi(w.y); v[8 * j + 4] = bf_lo(w.z); v[8 * j + 5] = bf_hi(w.z); v[8 * j + 6] = bf_lo(w.w); v[8 * j + 7] = bf_hi(w.w); } }
;         if (Y_) { float y[16]; float ss = 0.f;
; #pragma unroll
;             for (int j = 0; j < 2; ++j) { const u32x4 w = yw[j];
;                 y[8 * j + 0] = bf_lo(w.x); y[8 * j + 1] = bf_hi(w.x); y[8 * j + 2] = bf_lo(w.y); y[8 * j + 3] = bf_hi(w.y); y[8 * j + 4] = bf_lo(w.z); y[8 * j + 5] = bf_hi(w.z); y[8 * j + 6] = bf_lo(w.w); y[8 * j + 7] = bf_hi(w.w); }
; #pragma unroll
;             for (int i = 0; i < 16; ++i) ss += y[i] * y[i];
;             const float r = 1.0f / sqrtf(wave_sum(ss) * (1.f / DM) + EPS);
;             const GASF f32x4* gp = (const GASF f32x4*)gain_;
; #pragma unroll
;             for (int j = 0; j < 2; ++j) { const f32x4 a = gp[lane * 2 + 128 * j], b = gp[lane * 2 + 1 + 128 * j];
;                 v[8 * j + 0] += y[8 * j + 0] * r * a.x; v[8 * j + 1] += y[8 * j + 1] * r * a.y; v[8 * j + 2] += y[8 * j + 2] * r * a.z; v[8 * j + 3] += y[8 * j + 3] * r * a.w;
;                 v[8 * j + 4] += y[8 * j + 4] * r * b.x; v[8 * j + 5] += y[8 * j + 5] * r * b.y; v[8 * j + 6] += y[8 * j + 6] * r * b.z; v[8 * j + 7] += y[8 * j + 7] * r * b.w; } }
;         if (outf_) { GASF f32x4* p = (GASF f32x4*)(outf_ + (size_t)row * DM);
; #pragma unroll
;             for (int j = 0; j < 2; ++j) { p[lane * 2 + 128 * j] = (f32x4){v[8 * j + 0], v[8 * j + 1], v[8 * j + 2], v[8 * j + 3]}; p[lane * 2 + 1 + 128 * j] = (f32x4){v[8 * j + 4], v[8 * j + 5], v[8 * j + 6], v[8 * j + 7]}; } }
.LBB0_1269:
	s_waitcnt vmcnt(3)
	v_mov_b64_e32 v[18:19], v[14:15]
	v_mov_b64_e32 v[16:17], v[12:13]
	v_and_b32_e32 v54, 0xffff0000, v16
	v_lshlrev_b32_e32 v53, 16, v16
	v_mul_f32_e32 v16, v54, v54
	v_lshlrev_b32_e32 v55, 16, v17
	v_fmac_f32_e32 v16, v53, v53
	v_and_b32_e32 v56, 0xffff0000, v17
	v_fmac_f32_e32 v16, v55, v55
	v_lshlrev_b32_e32 v57, 16, v18
	v_fmac_f32_e32 v16, v56, v56
	v_and_b32_e32 v58, 0xffff0000, v18
	v_fmac_f32_e32 v16, v57, v57
	v_mov_b64_e32 v[22:23], v[10:11]
	v_lshlrev_b32_e32 v59, 16, v19
	v_fmac_f32_e32 v16, v58, v58
	v_mov_b64_e32 v[20:21], v[8:9]
	v_and_b32_e32 v60, 0xffff0000, v19
	v_fmac_f32_e32 v16, v59, v59
	v_lshlrev_b32_e32 v51, 16, v20
	v_fmac_f32_e32 v16, v60, v60
	v_and_b32_e32 v50, 0xffff0000, v20
	v_fmac_f32_e32 v16, v51, v51
	s_nop 0
	v_mov_b64_e32 v[30:31], v[6:7]
	v_lshlrev_b32_e32 v49, 16, v21
	v_fmac_f32_e32 v16, v50, v50
	v_mov_b64_e32 v[28:29], v[4:5]
	v_mov_b64_e32 v[46:47], v[2:3]
	v_and_b32_e32 v48, 0xffff0000, v21
	v_fmac_f32_e32 v16, v49, v49
	v_lshlrev_b32_e32 v41, 16, v28
	v_and_b32_e32 v43, 0xffff0000, v28
	v_lshlrev_b32_e32 v42, 16, v29
	v_and_b32_e32 v40, 0xffff0000, v29
	v_lshlrev_b32_e32 v29, 16, v47
	v_and_b32_e32 v28, 0xffff0000, v47
	v_lshlrev_b32_e32 v47, 16, v22
	v_fmac_f32_e32 v16, v48, v48
	v_mov_b64_e32 v[44:45], v[0:1]
	s_add_i32 s0, s0, s2
	s_min_i32 s20, s0, 0x7fff
	s_ashr_i32 s21, s20, 31
	s_lshl_b64 s[20:21], s[20:21], 11
	s_add_u32 s28, s4, s20
	s_addc_u32 s29, s7, s21
	s_add_u32 s20, s8, s20
	s_addc_u32 s21, s22, s21
	v_lshl_add_u64 v[8:9], s[20:21], 0, v[24:25]
	v_lshl_add_u64 v[0:1], s[28:29], 0, v[24:25]
	global_load_dwordx4 v[4:7], v[0:1], off
	s_nop 0
	global_load_dwordx4 v[0:3], v[0:1], off offset:1024
	s_nop 0
	global_load_dwordx4 v[12:15], v[8:9], off
	s_nop 0
	global_load_dwordx4 v[8:11], v[8:9], off offset:1024
	v_lshlrev_b32_e32 v39, 16, v30
	v_and_b32_e32 v38, 0xffff0000, v30
	v_lshlrev_b32_e32 v37, 16, v31
	v_and_b32_e32 v36, 0xffff0000, v31
	v_lshlrev_b32_e32 v31, 16, v46
	v_and_b32_e32 v30, 0xffff0000, v46
	v_and_b32_e32 v46, 0xffff0000, v22
	v_fmac_f32_e32 v16, v47, v47
	v_lshlrev_b32_e32 v33, 16, v45
	v_and_b32_e32 v32, 0xffff0000, v45
	v_lshlrev_b32_e32 v45, 16, v23
	v_fmac_f32_e32 v16, v46, v46
	v_lshlrev_b32_e32 v35, 16, v44
	v_and_b32_e32 v34, 0xffff0000, v44
	v_and_b32_e32 v44, 0xffff0000, v23
	v_fmac_f32_e32 v16, v45, v45
	v_fmac_f32_e32 v16, v44, v44
	ds_swizzle_b32 v17, v16 offset:swizzle(SWAP,1)
	s_waitcnt lgkmcnt(0)
	v_add_f32_e32 v16, v16, v17
	ds_swizzle_b32 v17, v16 offset:swizzle(SWAP,2)
	s_waitcnt lgkmcnt(0)
	v_add_f32_e32 v16, v16, v17
	ds_swizzle_b32 v17, v16 offset:swizzle(SWAP,4)
	s_waitcnt lgkmcnt(0)
	v_add_f32_e32 v16, v16, v17
	ds_swizzle_b32 v17, v16 offset:swizzle(SWAP,8)
	s_waitcnt lgkmcnt(0)
	v_add_f32_e32 v16, v16, v17
	ds_swizzle_b32 v17, v16 offset:swizzle(SWAP,16)
	s_waitcnt lgkmcnt(0)
	v_add_f32_e32 v16, v16, v17
	v_mov_b32_e32 v17, v16
	s_nop 1
	v_permlane32_swap_b32_e32 v16, v17
	v_add_f32_e32 v16, v16, v17
	v_fmamk_f32 v16, v16, 0x3a800000, v204
	v_cmp_gt_f32_e32 vcc, s81, v16
	v_mul_f32_e32 v17, 0x4f800000, v16
	s_nop 0
	v_cndmask_b32_e32 v16, v16, v17, vcc
	v_sqrt_f32_e32 v17, v16
	s_nop 0
	v_add_u32_e32 v18, -1, v17
	v_fma_f32 v19, -v18, v17, v16
	v_cmp_ge_f32_e64 s[42:43], 0, v19
	v_add_u32_e32 v19, 1, v17
	s_nop 0
	v_cndmask_b32_e64 v18, v17, v18, s[42:43]
	v_fma_f32 v17, -v19, v17, v16
	v_cmp_lt_f32_e64 s[42:43], 0, v17
	s_nop 1
	v_cndmask_b32_e64 v17, v18, v19, s[42:43]
	v_mul_f32_e32 v18, 0x37800000, v17
	v_cndmask_b32_e32 v17, v17, v18, vcc
	v_cmp_class_f32_e32 vcc, v16, v205
	s_nop 1
	v_cndmask_b32_e32 v16, v17, v16, vcc
	v_div_scale_f32 v17, s[20:21], v16, v16, 1.0
	v_rcp_f32_e32 v18, v17
	s_nop 0
	v_fma_f32 v19, -v17, v18, 1.0
	v_fmac_f32_e32 v18, v19, v18
	v_div_scale_f32 v19, vcc, 1.0, v16, 1.0
	v_mul_f32_e32 v20, v19, v18
	v_fma_f32 v21, -v17, v20, v19
	v_fmac_f32_e32 v20, v21, v18
	v_fma_f32 v17, -v17, v20, v19
	v_div_fmas_f32 v17, v17, v18, v20
	v_div_fixup_f32 v52, v17, v16, 1.0
	v_mul_f32_e32 v53, v52, v53
	v_mul_f32_e32 v51, v52, v51
	v_fmac_f32_e32 v41, v68, v53
	v_mul_f32_e32 v20, v52, v54
	v_fmac_f32_e32 v43, v69, v20
	v_mul_f32_e32 v20, v52, v55
	v_fmac_f32_e32 v42, v70, v20
	v_mul_f32_e32 v20, v52, v56
	v_fmac_f32_e32 v40, v71, v20
	v_mul_f32_e32 v20, v52, v57
	v_fmac_f32_e32 v39, v72, v20
	v_mul_f32_e32 v16, v52, v58
	v_fmac_f32_e32 v38, v73, v16
	v_mul_f32_e32 v16, v52, v59
	v_fmac_f32_e32 v37, v74, v16
	v_mul_f32_e32 v16, v52, v60
	v_fmac_f32_e32 v36, v75, v16
	v_fmac_f32_e32 v35, v76, v51
	v_mul_f32_e32 v20, v52, v50
	v_fmac_f32_e32 v34, v77, v20
	v_mul_f32_e32 v20, v52, v49
	v_fmac_f32_e32 v33, v78, v20
	v_mul_f32_e32 v22, v43, v43
	v_fmac_f32_e32 v22, v41, v41
	v_fmac_f32_e32 v22, v42, v42
	v_fmac_f32_e32 v22, v40, v40
	v_fmac_f32_e32 v22, v39, v39
	v_fmac_f32_e32 v22, v38, v38
	v_fmac_f32_e32 v22, v37, v37
	v_fmac_f32_e32 v22, v36, v36
	v_fmac_f32_e32 v22, v35, v35
	v_mul_f32_e32 v20, v52, v48
	v_fmac_f32_e32 v22, v34, v34
	v_fmac_f32_e32 v32, v79, v20
	v_mul_f32_e32 v20, v52, v47
	v_fmac_f32_e32 v22, v33, v33
	v_fmac_f32_e32 v31, v80, v20
	v_mul_f32_e32 v16, v52, v46
	v_fmac_f32_e32 v22, v32, v32
	v_fmac_f32_e32 v30, v81, v16
	v_mul_f32_e32 v16, v52, v45
	v_fmac_f32_e32 v22, v31, v31
	v_fmac_f32_e32 v29, v82, v16
	v_mul_f32_e32 v16, v52, v44
	v_fmac_f32_e32 v22, v30, v30
	v_fmac_f32_e32 v28, v83, v16
	v_cvt_pk_bf16_f32 v16, v41, v43
	v_lshl_add_u64 v[20:21], s[16:17], 0, v[24:25]
	v_fmac_f32_e32 v22, v29, v29
	v_cvt_pk_bf16_f32 v17, v42, v40
	v_cvt_pk_bf16_f32 v18, v39, v38
	v_cvt_pk_bf16_f32 v19, v37, v36
	global_store_dwordx4 v[20:21], v[16:19], off
	v_fmac_f32_e32 v22, v28, v28
	s_nop 0
	v_cvt_pk_bf16_f32 v16, v35, v34
	v_cvt_pk_bf16_f32 v17, v33, v32
	v_cvt_pk_bf16_f32 v18, v31, v30
	v_cvt_pk_bf16_f32 v19, v29, v28
	global_store_dwordx4 v[20:21], v[16:19], off offset:1024
	ds_swizzle_b32 v16, v22 offset:swizzle(SWAP,1)
	s_waitcnt lgkmcnt(0)
	v_add_f32_e32 v16, v22, v16
	ds_swizzle_b32 v17, v16 offset:swizzle(SWAP,2)
	s_waitcnt lgkmcnt(0)
	v_add_f32_e32 v16, v16, v17
	ds_swizzle_b32 v17, v16 offset:swizzle(SWAP,4)
	s_waitcnt lgkmcnt(0)
	v_add_f32_e32 v16, v16, v17
	ds_swizzle_b32 v17, v16 offset:swizzle(SWAP,8)
	s_waitcnt lgkmcnt(0)
	v_add_f32_e32 v16, v16, v17
	ds_swizzle_b32 v17, v16 offset:swizzle(SWAP,16)
	s_waitcnt lgkmcnt(0)
	v_add_f32_e32 v16, v16, v17
	v_mov_b32_e32 v17, v16
	s_nop 1
	v_permlane32_swap_b32_e32 v16, v17
	s_and_saveexec_b64 s[20:21], s[40:41]
	s_cbranch_execz .LBB0_1268
; #define GASF __attribute__((address_space(1)))
; __device__ __forceinline__ void resid_rows(const float* xf_, bf16_t* XB_, const bf16_t* Y_, const float* gain_, float* R_, float* outf_, int rows, int gw, int NGW, int lane) {
;     ...
;             ss = wave_sum(ss);
;             if (lane == 0) ((GASF float*)R_)[row] = 1.0f / sqrtf(ss * (1.f / DM) + EPS); }
	v_add_f32_e32 v16, v16, v17
	v_fmamk_f32 v16, v16, 0x3a800000, v204
	v_mul_f32_e32 v17, 0x4f800000, v16
	v_cmp_gt_f32_e32 vcc, s81, v16
	s_nop 1
	v_cndmask_b32_e32 v16, v16, v17, vcc
	v_sqrt_f32_e32 v17, v16
	s_nop 0
	v_add_u32_e32 v18, -1, v17
	v_fma_f32 v20, -v18, v17, v16
	v_add_u32_e32 v19, 1, v17
	v_cmp_ge_f32_e64 s[42:43], 0, v20
	s_nop 1
	v_cndmask_b32_e64 v18, v17, v18, s[42:43]
	v_fma_f32 v17, -v19, v17, v16
	v_cmp_lt_f32_e64 s[42:43], 0, v17
	s_nop 1
	v_cndmask_b32_e64 v17, v18, v19, s[42:43]
	v_mul_f32_e32 v18, 0x37800000, v17
	v_cndmask_b32_e32 v17, v17, v18, vcc
	v_cmp_class_f32_e32 vcc, v16, v205
	s_nop 1
	v_cndmask_b32_e32 v16, v17, v16, vcc
	v_div_scale_f32 v17, s[28:29], v16, v16, 1.0
	v_rcp_f32_e32 v18, v17
	s_nop 0
	v_fma_f32 v19, -v17, v18, 1.0
	v_fmac_f32_e32 v18, v19, v18
	v_div_scale_f32 v19, vcc, 1.0, v16, 1.0
	v_mul_f32_e32 v20, v19, v18
	v_fma_f32 v21, -v17, v20, v19
	v_fmac_f32_e32 v20, v21, v18
	v_fma_f32 v17, -v17, v20, v19
	v_div_fmas_f32 v17, v17, v18, v20
	v_div_fixup_f32 v16, v17, v16, 1.0
	global_store_dword v175, v16, s[12:13]
	s_branch .LBB0_1268
